# up-projection epilogue: per-row RMS scales (IEEE sqrt+div, 35 VALU each) computed once per phase and kept in registers with a row tag, instead of 8x per unit
# speedup vs baseline: 1.0060x; 1.0044x over previous
; #define PG8_STAGE(bufoff, gbase, voff) do { _Pragma("unroll") for (int _i = 0; _i < 2; ++_i) \
;         __builtin_amdgcn_global_load_lds((const unsigned*)((const char*)(gbase) + (voff)[_i]), (PG8_LAS unsigned*)(lds + (bufoff) + ldsw + _i * 8192), 16, 0, 0); } while (0)
; #define PG8_WAIT_V(n) asm volatile("s_waitcnt vmcnt(" #n ")" ::: "memory")
; #define PG8_BAR __builtin_amdgcn_s_barrier()
; template <class Epi, class Sched, bool ALIGN_EPI = false, bool SP2 = false>
; __device__ __forceinline__ void gemm_phase(PG8_LAS unsigned char* lds, const Gemm g, const Sched& S, const Epi& E) {
;     ...
;         PG8_STAGE(PG8_SB(0, 0), cB, voffB); PG8_STAGE(PG8_SB(0, 1), cB + hstep, voffB); PG8_STAGE(PG8_SA(0, 0), cA, voffA); PG8_STAGE(PG8_SA(0, 1), cA + hstep, voffA);
;         if (wr == 1) PG8_BAR;
;         PG8_WAIT_V(2); PG8_BAR;
;         PG8_STAGE(PG8_SB(1, 0), cB + kstep, voffB); PG8_STAGE(PG8_SA(1, 0), cA + kstep, voffA); PG8_STAGE(PG8_SB(1, 1), cB + hstep + kstep, voffB);
;         PG8_WAIT_V(6); PG8_BAR;
;     __device__ __forceinline__ void operator()(const f32x4 (&acc)[2][2][4][2], const Unit& u, int wr, int wc, int fr, int fq) const {
;     ...
;         const bool hb = (fr & 8) != 0;
;         const int srow0 = u.pm * BM + wr * 64 + (fr & 7), scol = u.pn * BM + wc * 64 + (hb ? 32 : 0) + 8 * fq;
.LBB0_700:
	s_add_u32 s10, s6, 0xf800000
	s_addc_u32 s11, s7, 0
	s_lshl_b32 s2, s2, 2
	s_add_u32 s2, s6, s2
	v_lshrrev_b32_e32 v9, 1, v8
	s_sext_i32_i16 s1, s4
	s_addc_u32 s4, s7, 0
	v_and_b32_e32 v9, 24, v9
	s_add_u32 s12, s2, 0x100000
	v_and_b32_e32 v142, 15, v8
	v_lshlrev_b32_e32 v10, 1, v9
	v_lshlrev_b32_e32 v11, 2, v8
	s_mov_b64 s[30:31], 0x80
	s_addc_u32 s13, s4, 0
	s_and_b32 s16, s5, 3
	v_lshl_or_b32 v10, v142, 6, v10
	s_lshl_b32 s2, s14, 13
	v_and_b32_e32 v11, 32, v11
	s_add_i32 m0, s58, 0x18000
	v_lshl_add_u64 v[6:7], v[6:7], 0, s[30:31]
	s_lshl_b32 s62, s14, 6
	v_bitop3_b32 v12, v10, s2, v11 bitop3:0xde
	s_lshl_b32 s2, s16, 12
	s_waitcnt vmcnt(2)
	s_barrier
	global_load_lds_dwordx4 v[6:7], off
	v_lshl_add_u64 v[4:5], v[4:5], 0, s[30:31]
	s_add_i32 m0, s58, 0x1a000
	s_add_i32 s63, s58, 0x8000
	s_add_i32 s64, s58, 0xa000
	global_load_lds_dwordx4 v[4:5], off
	v_lshl_add_u64 v[0:1], v[0:1], 0, s[30:31]
	s_mov_b32 m0, s63
	s_add_u32 s4, s26, 0x80080
	global_load_lds_dwordx4 v[0:1], off
	v_lshl_add_u64 v[0:1], v[2:3], 0, s[30:31]
	s_mov_b32 m0, s64
	s_addc_u32 s5, s27, 0
	global_load_lds_dwordx4 v[0:1], off
	s_add_i32 m0, s58, 0x1c000
	v_lshl_add_u64 v[0:1], s[4:5], 0, v[172:173]
	global_load_lds_dwordx4 v[0:1], off
	v_lshl_add_u64 v[0:1], s[4:5], 0, v[132:133]
	s_add_i32 m0, s58, 0x1e000
	v_bitop3_b32 v143, v10, s2, v11 bitop3:0xde
	global_load_lds_dwordx4 v[0:1], off
	s_waitcnt vmcnt(6)
	s_cmpk_lt_u32 s3, 0x100
	v_cmp_lt_u32_e64 s[2:3], 7, v142
	s_cselect_b64 s[14:15], -1, 0
	s_lshl_b32 s4, s16, 6
	v_cndmask_b32_e64 v0, 0, 32, s[2:3]
	v_and_b32_e32 v144, 7, v8
	s_mov_b32 s65, 0
	v_or3_b32 v145, s4, v0, v9
	v_add_u32_e32 v146, 0, v12
	s_barrier
	v_mov_b32_e32 v243, -1
	s_branch .LBB0_703

; __device__ __forceinline__ float rs_of(const float* ss, int row) { return 1.0f / sqrtf(ss[row] * (1.0f / 2048.0f) + 1e-5f); }
;     __device__ __forceinline__ void operator()(const f32x4 (&acc)[2][2][4][2], const Unit& u, int wr, int wc, int fr, int fq) const {
;         const int row0 = u.pm * BM + wr * 64 + fr;
;         const bool hb = (fr & 8) != 0;
;         const int srow0 = u.pm * BM + wr * 64 + (fr & 7), scol = u.pn * BM + wc * 64 + (hb ? 32 : 0) + 8 * fq;
;         const f32x4 z = {0.f, 0.f, 0.f, 0.f};
; #pragma unroll
;         for (int ai = 0; ai < 2; ++ai)
; #pragma unroll
;             for (int m = 0; m < 4; ++m) {
;                 const int row = row0 + ai * HALF + m * 16; const float rr = ss ? rs_of(ss, row) : 1.0f;
.LBB0_715:
	s_lshl_b32 s0, s0, 8
	s_add_i32 s0, s0, s62
	v_or_b32_e32 v134, s0, v142
	v_ashrrev_i32_e32 v135, 31, v134
	v_lshl_add_u64 v[134:135], v[134:135], 2, s[12:13]
	s_and_b64 vcc, exec, s[14:15]
	s_cbranch_vccz .LBB0_717
	s_barrier
.LBB0_717:
	v_or_b32_e32 v136, s0, v144
	v_lshl_or_b32 v138, s1, 8, v145
	v_cmp_eq_u32_e32 vcc, s0, v243
	s_cbranch_vccnz .Lrr_hit
	global_load_dword v234, v[134:135], off
	global_load_dword v235, v[134:135], off offset:64
	global_load_dword v236, v[134:135], off offset:128
	global_load_dword v237, v[134:135], off offset:192
	global_load_dword v238, v[134:135], off offset:512
	global_load_dword v239, v[134:135], off offset:576
	global_load_dword v240, v[134:135], off offset:640
	global_load_dword v241, v[134:135], off offset:704
	v_mov_b32_e32 v243, s0
	s_waitcnt vmcnt(0)
	v_fmamk_f32 v242, v234, 0x3a000000, v205
	v_mul_f32_e32 v224, 0x4f800000, v242
	v_cmp_gt_f32_e32 vcc, s83, v242
	s_nop 1
	v_cndmask_b32_e32 v242, v242, v224, vcc
	v_sqrt_f32_e32 v224, v242
	s_nop 1
	v_add_u32_e32 v225, -1, v224
	v_add_u32_e32 v226, 1, v224
	v_fma_f32 v227, -v225, v224, v242
	v_fma_f32 v228, -v226, v224, v242
	v_cmp_ge_f32_e64 s[0:1], 0, v227
	s_nop 1
	v_cndmask_b32_e64 v224, v224, v225, s[0:1]
	v_cmp_lt_f32_e64 s[0:1], 0, v228
	s_nop 1
	v_cndmask_b32_e64 v224, v224, v226, s[0:1]
	v_mul_f32_e32 v225, 0x37800000, v224
	v_cndmask_b32_e32 v224, v224, v225, vcc
	v_cmp_class_f32_e32 vcc, v242, v206
	s_nop 1
	v_cndmask_b32_e32 v242, v224, v242, vcc
	v_div_scale_f32 v224, s[0:1], v242, v242, 1.0
	v_rcp_f32_e32 v226, v224
	v_div_scale_f32 v225, vcc, 1.0, v242, 1.0
	v_fma_f32 v227, -v224, v226, 1.0
	v_fmac_f32_e32 v226, v227, v226
	v_mul_f32_e32 v227, v225, v226
	v_fma_f32 v228, -v224, v227, v225
	v_fmac_f32_e32 v227, v228, v226
	v_fma_f32 v224, -v224, v227, v225
	v_div_fmas_f32 v224, v224, v226, v227
	v_div_fixup_f32 v234, v224, v242, 1.0
	v_fmamk_f32 v242, v235, 0x3a000000, v205
	v_mul_f32_e32 v224, 0x4f800000, v242
	v_cmp_gt_f32_e32 vcc, s83, v242
	s_nop 1
	v_cndmask_b32_e32 v242, v242, v224, vcc
	v_sqrt_f32_e32 v224, v242
	s_nop 1
	v_add_u32_e32 v225, -1, v224
	v_add_u32_e32 v226, 1, v224
	v_fma_f32 v227, -v225, v224, v242
	v_fma_f32 v228, -v226, v224, v242
	v_cmp_ge_f32_e64 s[0:1], 0, v227
	s_nop 1
	v_cndmask_b32_e64 v224, v224, v225, s[0:1]
	v_cmp_lt_f32_e64 s[0:1], 0, v228
	s_nop 1
	v_cndmask_b32_e64 v224, v224, v226, s[0:1]
	v_mul_f32_e32 v225, 0x37800000, v224
	v_cndmask_b32_e32 v224, v224, v225, vcc
	v_cmp_class_f32_e32 vcc, v242, v206
	s_nop 1
	v_cndmask_b32_e32 v242, v224, v242, vcc
	v_div_scale_f32 v224, s[0:1], v242, v242, 1.0
	v_rcp_f32_e32 v226, v224
	v_div_scale_f32 v225, vcc, 1.0, v242, 1.0
	v_fma_f32 v227, -v224, v226, 1.0
	v_fmac_f32_e32 v226, v227, v226
	v_mul_f32_e32 v227, v225, v226
	v_fma_f32 v228, -v224, v227, v225
	v_fmac_f32_e32 v227, v228, v226
	v_fma_f32 v224, -v224, v227, v225
	v_div_fmas_f32 v224, v224, v226, v227
	v_div_fixup_f32 v235, v224, v242, 1.0
	v_fmamk_f32 v242, v236, 0x3a000000, v205
	v_mul_f32_e32 v224, 0x4f800000, v242
	v_cmp_gt_f32_e32 vcc, s83, v242
	s_nop 1
	v_cndmask_b32_e32 v242, v242, v224, vcc
	v_sqrt_f32_e32 v224, v242
	s_nop 1
	v_add_u32_e32 v225, -1, v224
	v_add_u32_e32 v226, 1, v224
	v_fma_f32 v227, -v225, v224, v242
	v_fma_f32 v228, -v226, v224, v242
	v_cmp_ge_f32_e64 s[0:1], 0, v227
	s_nop 1
	v_cndmask_b32_e64 v224, v224, v225, s[0:1]
	v_cmp_lt_f32_e64 s[0:1], 0, v228
	s_nop 1
	v_cndmask_b32_e64 v224, v224, v226, s[0:1]
	v_mul_f32_e32 v225, 0x37800000, v224
	v_cndmask_b32_e32 v224, v224, v225, vcc
	v_cmp_class_f32_e32 vcc, v242, v206
	s_nop 1
	v_cndmask_b32_e32 v242, v224, v242, vcc
	v_div_scale_f32 v224, s[0:1], v242, v242, 1.0
	v_rcp_f32_e32 v226, v224
	v_div_scale_f32 v225, vcc, 1.0, v242, 1.0
	v_fma_f32 v227, -v224, v226, 1.0
	v_fmac_f32_e32 v226, v227, v226
	v_mul_f32_e32 v227, v225, v226
	v_fma_f32 v228, -v224, v227, v225
	v_fmac_f32_e32 v227, v228, v226
	v_fma_f32 v224, -v224, v227, v225
	v_div_fmas_f32 v224, v224, v226, v227
	v_div_fixup_f32 v236, v224, v242, 1.0
	v_fmamk_f32 v242, v237, 0x3a000000, v205
	v_mul_f32_e32 v224, 0x4f800000, v242
	v_cmp_gt_f32_e32 vcc, s83, v242
	s_nop 1
	v_cndmask_b32_e32 v242, v242, v224, vcc
	v_sqrt_f32_e32 v224, v242
	s_nop 1
	v_add_u32_e32 v225, -1, v224
	v_add_u32_e32 v226, 1, v224
	v_fma_f32 v227, -v225, v224, v242
	v_fma_f32 v228, -v226, v224, v242
	v_cmp_ge_f32_e64 s[0:1], 0, v227
	s_nop 1
	v_cndmask_b32_e64 v224, v224, v225, s[0:1]
	v_cmp_lt_f32_e64 s[0:1], 0, v228
	s_nop 1
	v_cndmask_b32_e64 v224, v224, v226, s[0:1]
	v_mul_f32_e32 v225, 0x37800000, v224
	v_cndmask_b32_e32 v224, v224, v225, vcc
	v_cmp_class_f32_e32 vcc, v242, v206
	s_nop 1
	v_cndmask_b32_e32 v242, v224, v242, vcc
	v_div_scale_f32 v224, s[0:1], v242, v242, 1.0
	v_rcp_f32_e32 v226, v224
	v_div_scale_f32 v225, vcc, 1.0, v242, 1.0
	v_fma_f32 v227, -v224, v226, 1.0
	v_fmac_f32_e32 v226, v227, v226
	v_mul_f32_e32 v227, v225, v226
	v_fma_f32 v228, -v224, v227, v225
	v_fmac_f32_e32 v227, v228, v226
	v_fma_f32 v224, -v224, v227, v225
	v_div_fmas_f32 v224, v224, v226, v227
	v_div_fixup_f32 v237, v224, v242, 1.0
	v_fmamk_f32 v242, v238, 0x3a000000, v205
	v_mul_f32_e32 v224, 0x4f800000, v242
	v_cmp_gt_f32_e32 vcc, s83, v242
	s_nop 1
	v_cndmask_b32_e32 v242, v242, v224, vcc
	v_sqrt_f32_e32 v224, v242
	s_nop 1
	v_add_u32_e32 v225, -1, v224
	v_add_u32_e32 v226, 1, v224
	v_fma_f32 v227, -v225, v224, v242
	v_fma_f32 v228, -v226, v224, v242
	v_cmp_ge_f32_e64 s[0:1], 0, v227
	s_nop 1
	v_cndmask_b32_e64 v224, v224, v225, s[0:1]
	v_cmp_lt_f32_e64 s[0:1], 0, v228
	s_nop 1
	v_cndmask_b32_e64 v224, v224, v226, s[0:1]
	v_mul_f32_e32 v225, 0x37800000, v224
	v_cndmask_b32_e32 v224, v224, v225, vcc
; __device__ __forceinline__ u32x4 pack8(f32x4 a, f32x4 b) { u32x4 w; w.x = cvt_pk_bf16(a[0], a[1]); w.y = cvt_pk_bf16(a[2], a[3]); w.z = cvt_pk_bf16(b[0], b[1]); w.w = cvt_pk_bf16(b[2], b[3]); return w; }
; __device__ __forceinline__ float rs_of(const float* ss, int row) { return 1.0f / sqrtf(ss[row] * (1.0f / 2048.0f) + 1e-5f); }
;     __device__ __forceinline__ void operator()(const f32x4 (&acc)[2][2][4][2], const Unit& u, int wr, int wc, int fr, int fq) const {
;     ...
;                 const int row = row0 + ai * HALF + m * 16; const float rr = ss ? rs_of(ss, row) : 1.0f;
;                 u32x4 v[2];
; #pragma unroll
;                 for (int bj = 0; bj < 2; ++bj) {
;                     f32x4 a = __builtin_elementwise_max(acc[ai][bj][m][0], z) * rr, b = __builtin_elementwise_max(acc[ai][bj][m][1], z) * rr;
;                     v[bj] = pack8(a * a, b * b);
	v_cmp_class_f32_e32 vcc, v242, v206
	s_nop 1
	v_cndmask_b32_e32 v242, v224, v242, vcc
	v_div_scale_f32 v224, s[0:1], v242, v242, 1.0
	v_rcp_f32_e32 v226, v224
	v_div_scale_f32 v225, vcc, 1.0, v242, 1.0
	v_fma_f32 v227, -v224, v226, 1.0
	v_fmac_f32_e32 v226, v227, v226
	v_mul_f32_e32 v227, v225, v226
	v_fma_f32 v228, -v224, v227, v225
	v_fmac_f32_e32 v227, v228, v226
	v_fma_f32 v224, -v224, v227, v225
	v_div_fmas_f32 v224, v224, v226, v227
	v_div_fixup_f32 v238, v224, v242, 1.0
	v_fmamk_f32 v242, v239, 0x3a000000, v205
	v_mul_f32_e32 v224, 0x4f800000, v242
	v_cmp_gt_f32_e32 vcc, s83, v242
	s_nop 1
	v_cndmask_b32_e32 v242, v242, v224, vcc
	v_sqrt_f32_e32 v224, v242
	s_nop 1
	v_add_u32_e32 v225, -1, v224
	v_add_u32_e32 v226, 1, v224
	v_fma_f32 v227, -v225, v224, v242
	v_fma_f32 v228, -v226, v224, v242
	v_cmp_ge_f32_e64 s[0:1], 0, v227
	s_nop 1
	v_cndmask_b32_e64 v224, v224, v225, s[0:1]
	v_cmp_lt_f32_e64 s[0:1], 0, v228
	s_nop 1
	v_cndmask_b32_e64 v224, v224, v226, s[0:1]
	v_mul_f32_e32 v225, 0x37800000, v224
	v_cndmask_b32_e32 v224, v224, v225, vcc
	v_cmp_class_f32_e32 vcc, v242, v206
	s_nop 1
	v_cndmask_b32_e32 v242, v224, v242, vcc
	v_div_scale_f32 v224, s[0:1], v242, v242, 1.0
	v_rcp_f32_e32 v226, v224
	v_div_scale_f32 v225, vcc, 1.0, v242, 1.0
	v_fma_f32 v227, -v224, v226, 1.0
	v_fmac_f32_e32 v226, v227, v226
	v_mul_f32_e32 v227, v225, v226
	v_fma_f32 v228, -v224, v227, v225
	v_fmac_f32_e32 v227, v228, v226
	v_fma_f32 v224, -v224, v227, v225
	v_div_fmas_f32 v224, v224, v226, v227
	v_div_fixup_f32 v239, v224, v242, 1.0
	v_fmamk_f32 v242, v240, 0x3a000000, v205
	v_mul_f32_e32 v224, 0x4f800000, v242
	v_cmp_gt_f32_e32 vcc, s83, v242
	s_nop 1
	v_cndmask_b32_e32 v242, v242, v224, vcc
	v_sqrt_f32_e32 v224, v242
	s_nop 1
	v_add_u32_e32 v225, -1, v224
	v_add_u32_e32 v226, 1, v224
	v_fma_f32 v227, -v225, v224, v242
	v_fma_f32 v228, -v226, v224, v242
	v_cmp_ge_f32_e64 s[0:1], 0, v227
	s_nop 1
	v_cndmask_b32_e64 v224, v224, v225, s[0:1]
	v_cmp_lt_f32_e64 s[0:1], 0, v228
	s_nop 1
	v_cndmask_b32_e64 v224, v224, v226, s[0:1]
	v_mul_f32_e32 v225, 0x37800000, v224
	v_cndmask_b32_e32 v224, v224, v225, vcc
	v_cmp_class_f32_e32 vcc, v242, v206
	s_nop 1
	v_cndmask_b32_e32 v242, v224, v242, vcc
	v_div_scale_f32 v224, s[0:1], v242, v242, 1.0
	v_rcp_f32_e32 v226, v224
	v_div_scale_f32 v225, vcc, 1.0, v242, 1.0
	v_fma_f32 v227, -v224, v226, 1.0
	v_fmac_f32_e32 v226, v227, v226
	v_mul_f32_e32 v227, v225, v226
	v_fma_f32 v228, -v224, v227, v225
	v_fmac_f32_e32 v227, v228, v226
	v_fma_f32 v224, -v224, v227, v225
	v_div_fmas_f32 v224, v224, v226, v227
	v_div_fixup_f32 v240, v224, v242, 1.0
	v_fmamk_f32 v242, v241, 0x3a000000, v205
	v_mul_f32_e32 v224, 0x4f800000, v242
	v_cmp_gt_f32_e32 vcc, s83, v242
	s_nop 1
	v_cndmask_b32_e32 v242, v242, v224, vcc
	v_sqrt_f32_e32 v224, v242
	s_nop 1
	v_add_u32_e32 v225, -1, v224
	v_add_u32_e32 v226, 1, v224
	v_fma_f32 v227, -v225, v224, v242
	v_fma_f32 v228, -v226, v224, v242
	v_cmp_ge_f32_e64 s[0:1], 0, v227
	s_nop 1
	v_cndmask_b32_e64 v224, v224, v225, s[0:1]
	v_cmp_lt_f32_e64 s[0:1], 0, v228
	s_nop 1
	v_cndmask_b32_e64 v224, v224, v226, s[0:1]
	v_mul_f32_e32 v225, 0x37800000, v224
	v_cndmask_b32_e32 v224, v224, v225, vcc
	v_cmp_class_f32_e32 vcc, v242, v206
	s_nop 1
	v_cndmask_b32_e32 v242, v224, v242, vcc
	v_div_scale_f32 v224, s[0:1], v242, v242, 1.0
	v_rcp_f32_e32 v226, v224
	v_div_scale_f32 v225, vcc, 1.0, v242, 1.0
	v_fma_f32 v227, -v224, v226, 1.0
	v_fmac_f32_e32 v226, v227, v226
	v_mul_f32_e32 v227, v225, v226
	v_fma_f32 v228, -v224, v227, v225
	v_fmac_f32_e32 v227, v228, v226
	v_fma_f32 v224, -v224, v227, v225
	v_div_fmas_f32 v224, v224, v226, v227
	v_div_fixup_f32 v241, v224, v242, 1.0
.Lrr_hit:
	v_max_f32_e32 v127, 0, v127
	v_max_f32_e32 v126, 0, v126
	v_max_f32_e32 v125, 0, v125
	v_max_f32_e32 v124, 0, v124
	v_max_f32_e32 v123, 0, v123
	v_max_f32_e32 v122, 0, v122
	v_max_f32_e32 v121, 0, v121
	v_max_f32_e32 v120, 0, v120
	v_max_f32_e32 v115, 0, v115
	v_max_f32_e32 v114, 0, v114
	v_max_f32_e32 v113, 0, v113
	v_max_f32_e32 v112, 0, v112
	v_max_f32_e32 v119, 0, v119
	v_max_f32_e32 v118, 0, v118
	v_max_f32_e32 v117, 0, v117
	v_max_f32_e32 v116, 0, v116
	v_ashrrev_i32_e32 v139, 31, v138
	v_max_f32_e32 v111, 0, v111
	v_max_f32_e32 v110, 0, v110
	v_max_f32_e32 v109, 0, v109
	v_max_f32_e32 v108, 0, v108
	v_max_f32_e32 v107, 0, v107
	v_max_f32_e32 v106, 0, v106
	v_max_f32_e32 v105, 0, v105
	v_max_f32_e32 v104, 0, v104
	v_max_f32_e32 v97, 0, v97
	v_max_f32_e32 v96, 0, v96
	v_max_f32_e32 v103, 0, v103
	v_max_f32_e32 v102, 0, v102
	v_max_f32_e32 v101, 0, v101
	v_max_f32_e32 v100, 0, v100
	v_max_f32_e32 v99, 0, v99
	v_max_f32_e32 v98, 0, v98
	v_max_f32_e32 v95, 0, v95
	v_max_f32_e32 v94, 0, v94
	v_max_f32_e32 v93, 0, v93
	v_max_f32_e32 v92, 0, v92
	v_max_f32_e32 v91, 0, v91
	v_max_f32_e32 v90, 0, v90
	v_max_f32_e32 v89, 0, v89
	v_max_f32_e32 v88, 0, v88
	v_max_f32_e32 v87, v87, v87
	v_max_f32_e32 v86, v86, v86
	v_max_f32_e32 v85, v85, v85
	v_max_f32_e32 v84, v84, v84
	v_max_f32_e32 v83, v83, v83
	v_max_f32_e32 v82, v82, v82
	v_mov_b32_e32 v140, v234
	v_pk_mul_f32 v[124:125], v[124:125], v[140:141] op_sel_hi:[1,0]
	v_pk_mul_f32 v[126:127], v[126:127], v[140:141] op_sel_hi:[1,0]
	v_pk_mul_f32 v[120:121], v[120:121], v[140:141] op_sel_hi:[1,0]
	v_pk_mul_f32 v[122:123], v[122:123], v[140:141] op_sel_hi:[1,0]
	v_pk_mul_f32 v[112:113], v[112:113], v[140:141] op_sel_hi:[1,0]
	v_pk_mul_f32 v[114:115], v[114:115], v[140:141] op_sel_hi:[1,0]
	v_pk_mul_f32 v[126:127], v[126:127], v[126:127]
	v_pk_mul_f32 v[124:125], v[124:125], v[124:125]
	v_pk_mul_f32 v[122:123], v[122:123], v[122:123]
	v_pk_mul_f32 v[120:121], v[120:121], v[120:121]
; __device__ __forceinline__ u32x4 pack8(f32x4 a, f32x4 b) { u32x4 w; w.x = cvt_pk_bf16(a[0], a[1]); w.y = cvt_pk_bf16(a[2], a[3]); w.z = cvt_pk_bf16(b[0], b[1]); w.w = cvt_pk_bf16(b[2], b[3]); return w; }
; __device__ __forceinline__ float rs_of(const float* ss, int row) { return 1.0f / sqrtf(ss[row] * (1.0f / 2048.0f) + 1e-5f); }
;     __device__ __forceinline__ void operator()(const f32x4 (&acc)[2][2][4][2], const Unit& u, int wr, int wc, int fr, int fq) const {
;     ...
;             for (int m = 0; m < 4; ++m) {
;                 const int row = row0 + ai * HALF + m * 16; const float rr = ss ? rs_of(ss, row) : 1.0f;
;                 u32x4 v[2];
; #pragma unroll
;                 for (int bj = 0; bj < 2; ++bj) {
;                     f32x4 a = __builtin_elementwise_max(acc[ai][bj][m][0], z) * rr, b = __builtin_elementwise_max(acc[ai][bj][m][1], z) * rr;
;                     v[bj] = pack8(a * a, b * b);
;                 }
;                 line_xchg(v[0], v[1], hb);
;                 bf16_t* p = O + (size_t)(srow0 + ai * HALF + m * 16) * ldc + scol;
;                 __builtin_nontemporal_store(v[0], (u32x4*)p); __builtin_nontemporal_store(v[1], (u32x4*)(p + (size_t)8 * ldc));
;             }
	v_pk_mul_f32 v[116:117], v[116:117], v[140:141] op_sel_hi:[1,0]
	v_pk_mul_f32 v[118:119], v[118:119], v[140:141] op_sel_hi:[1,0]
	v_pk_mul_f32 v[114:115], v[114:115], v[114:115]
	v_pk_mul_f32 v[112:113], v[112:113], v[112:113]
	v_cvt_pk_bf16_f32 v124, v124, v125
	v_cvt_pk_bf16_f32 v125, v126, v127
	v_cvt_pk_bf16_f32 v120, v120, v121
	v_cvt_pk_bf16_f32 v121, v122, v123
	v_pk_mul_f32 v[118:119], v[118:119], v[118:119]
	v_pk_mul_f32 v[116:117], v[116:117], v[116:117]
	v_max_f32_e32 v81, 0, v81
	v_cvt_pk_bf16_f32 v122, v116, v117
	v_cvt_pk_bf16_f32 v123, v118, v119
	v_cvt_pk_bf16_f32 v126, v112, v113
	v_cvt_pk_bf16_f32 v115, v114, v115
	v_max_f32_e32 v80, 0, v80
	v_cndmask_b32_e64 v113, v126, v120, s[2:3]
	v_cndmask_b32_e64 v114, v123, v125, s[2:3]
	v_cndmask_b32_e64 v112, v115, v121, s[2:3]
	v_mov_b32_dpp v137, v113 row_ror:8 row_mask:0xf bank_mask:0xf
	v_mov_b32_dpp v114, v114 row_ror:8 row_mask:0xf bank_mask:0xf
	v_cndmask_b32_e64 v116, v122, v124, s[2:3]
	v_mov_b32_dpp v140, v112 row_ror:8 row_mask:0xf bank_mask:0xf
	v_cndmask_b32_e64 v117, v125, v114, s[2:3]
	v_cndmask_b32_e64 v118, v120, v137, s[2:3]
	v_cndmask_b32_e64 v113, v114, v123, s[2:3]
	v_cndmask_b32_e64 v114, v137, v126, s[2:3]
	v_ashrrev_i32_e32 v137, 31, v136
	v_mov_b32_dpp v127, v116 row_ror:8 row_mask:0xf bank_mask:0xf
	v_cndmask_b32_e64 v119, v121, v140, s[2:3]
	v_lshlrev_b64 v[120:121], 14, v[136:137]
	v_cndmask_b32_e64 v112, v127, v122, s[2:3]
	v_lshl_add_u64 v[120:121], s[10:11], 0, v[120:121]
	v_lshlrev_b64 v[122:123], 1, v[138:139]
	v_cndmask_b32_e64 v116, v124, v127, s[2:3]
	v_lshl_add_u64 v[120:121], v[120:121], 0, v[122:123]
	global_store_dwordx4 v[120:121], v[116:119], off nt
	v_cndmask_b32_e64 v115, v140, v115, s[2:3]
	v_max_f32_e32 v87, 0, v87
	v_add_co_u32_e32 v116, vcc, s79, v120
	v_max_f32_e32 v86, 0, v86
	s_nop 0
	v_addc_co_u32_e32 v117, vcc, 0, v121, vcc
	global_store_dwordx4 v[116:117], v[112:115], off nt
	v_max_f32_e32 v85, 0, v85
	v_max_f32_e32 v84, 0, v84
	v_max_f32_e32 v83, 0, v83
	v_max_f32_e32 v82, 0, v82
	v_max_f32_e32 v79, v79, v79
	v_max_f32_e32 v79, 0, v79
	v_max_f32_e32 v78, 0, v78
	v_max_f32_e32 v77, 0, v77
	v_max_f32_e32 v76, 0, v76
	v_max_f32_e32 v75, 0, v75
	v_max_f32_e32 v74, 0, v74
	v_max_f32_e32 v73, 0, v73
	v_max_f32_e32 v72, 0, v72
	v_max_f32_e32 v65, 0, v65
	v_max_f32_e32 v64, 0, v64
	v_max_f32_e32 v71, 0, v71
	v_max_f32_e32 v70, 0, v70
	v_max_f32_e32 v69, 0, v69
	v_max_f32_e32 v68, 0, v68
	v_max_f32_e32 v67, 0, v67
	v_max_f32_e32 v66, 0, v66
	v_max_f32_e32 v63, 0, v63
	v_max_f32_e32 v62, 0, v62
	v_max_f32_e32 v61, 0, v61
	v_max_f32_e32 v60, 0, v60
	v_max_f32_e32 v59, 0, v59
	v_max_f32_e32 v58, 0, v58
	v_max_f32_e32 v57, 0, v57
	v_max_f32_e32 v56, 0, v56
	v_max_f32_e32 v49, 0, v49
	v_max_f32_e32 v48, 0, v48
	v_max_f32_e32 v55, 0, v55
	v_max_f32_e32 v54, 0, v54
	v_max_f32_e32 v53, 0, v53
	v_max_f32_e32 v52, 0, v52
	v_max_f32_e32 v51, 0, v51
	v_max_f32_e32 v50, 0, v50
	v_max_f32_e32 v46, v46, v46
	v_max_f32_e32 v45, 0, v45
	v_max_f32_e32 v44, 0, v44
	v_max_f32_e32 v43, v43, v43
	v_max_f32_e32 v42, v42, v42
	v_max_f32_e32 v41, 0, v41
	v_max_f32_e32 v40, 0, v40
	v_max_f32_e32 v39, 0, v39
	v_max_f32_e32 v38, 0, v38
	v_max_f32_e32 v37, 0, v37
	v_max_f32_e32 v36, 0, v36
	v_max_f32_e32 v35, v35, v35
	v_mov_b32_e32 v112, v235
	v_pk_mul_f32 v[108:109], v[108:109], v[112:113] op_sel_hi:[1,0]
	v_pk_mul_f32 v[110:111], v[110:111], v[112:113] op_sel_hi:[1,0]
	v_pk_mul_f32 v[104:105], v[104:105], v[112:113] op_sel_hi:[1,0]
	v_pk_mul_f32 v[106:107], v[106:107], v[112:113] op_sel_hi:[1,0]
	v_pk_mul_f32 v[96:97], v[96:97], v[112:113] op_sel_hi:[1,0]
	v_pk_mul_f32 v[110:111], v[110:111], v[110:111]
	v_pk_mul_f32 v[108:109], v[108:109], v[108:109]
	v_pk_mul_f32 v[106:107], v[106:107], v[106:107]
	v_pk_mul_f32 v[104:105], v[104:105], v[104:105]
	v_pk_mul_f32 v[100:101], v[100:101], v[112:113] op_sel_hi:[1,0]
	v_pk_mul_f32 v[102:103], v[102:103], v[112:113] op_sel_hi:[1,0]
	v_pk_mul_f32 v[98:99], v[98:99], v[112:113] op_sel_hi:[1,0]
	v_pk_mul_f32 v[96:97], v[96:97], v[96:97]
	v_cvt_pk_bf16_f32 v108, v108, v109
	v_cvt_pk_bf16_f32 v109, v110, v111
	v_cvt_pk_bf16_f32 v104, v104, v105
	v_cvt_pk_bf16_f32 v105, v106, v107
	v_pk_mul_f32 v[102:103], v[102:103], v[102:103]
	v_pk_mul_f32 v[100:101], v[100:101], v[100:101]
	v_pk_mul_f32 v[98:99], v[98:99], v[98:99]
	v_cvt_pk_bf16_f32 v106, v100, v101
	v_cvt_pk_bf16_f32 v107, v102, v103
	v_cvt_pk_bf16_f32 v110, v96, v97
	v_max_f32_e32 v34, v34, v34
	v_cndmask_b32_e64 v97, v110, v104, s[2:3]
	v_cvt_pk_bf16_f32 v99, v98, v99
	v_cndmask_b32_e64 v98, v107, v109, s[2:3]
	v_cndmask_b32_e64 v96, v99, v105, s[2:3]
	v_mov_b32_dpp v112, v97 row_ror:8 row_mask:0xf bank_mask:0xf
	v_cndmask_b32_e64 v102, v104, v112, s[2:3]
	v_mov_b32_dpp v113, v96 row_ror:8 row_mask:0xf bank_mask:0xf
	v_or_b32_e32 v104, 16, v136
	v_cndmask_b32_e64 v103, v105, v113, s[2:3]
	v_ashrrev_i32_e32 v105, 31, v104
	v_cndmask_b32_e64 v100, v106, v108, s[2:3]
	v_lshlrev_b64 v[104:105], 14, v[104:105]
	v_mov_b32_dpp v98, v98 row_ror:8 row_mask:0xf bank_mask:0xf
	v_mov_b32_dpp v111, v100 row_ror:8 row_mask:0xf bank_mask:0xf
	v_lshl_add_u64 v[104:105], s[10:11], 0, v[104:105]
	v_cndmask_b32_e64 v100, v108, v111, s[2:3]
	v_cndmask_b32_e64 v101, v109, v98, s[2:3]
	v_lshl_add_u64 v[104:105], v[104:105], 0, v[122:123]
	global_store_dwordx4 v[104:105], v[100:103], off nt
	v_cndmask_b32_e64 v96, v111, v106, s[2:3]
	v_cndmask_b32_e64 v97, v98, v107, s[2:3]
	v_add_co_u32_e32 v100, vcc, s79, v104
	v_cndmask_b32_e64 v98, v112, v110, s[2:3]
	v_cndmask_b32_e64 v99, v113, v99, s[2:3]
	v_addc_co_u32_e32 v101, vcc, 0, v105, vcc
	global_store_dwordx4 v[100:101], v[96:99], off nt
; __device__ __forceinline__ u32x4 pack8(f32x4 a, f32x4 b) { u32x4 w; w.x = cvt_pk_bf16(a[0], a[1]); w.y = cvt_pk_bf16(a[2], a[3]); w.z = cvt_pk_bf16(b[0], b[1]); w.w = cvt_pk_bf16(b[2], b[3]); return w; }
; __device__ __forceinline__ float rs_of(const float* ss, int row) { return 1.0f / sqrtf(ss[row] * (1.0f / 2048.0f) + 1e-5f); }
;     __device__ __forceinline__ void operator()(const f32x4 (&acc)[2][2][4][2], const Unit& u, int wr, int wc, int fr, int fq) const {
;     ...
;             for (int m = 0; m < 4; ++m) {
;                 const int row = row0 + ai * HALF + m * 16; const float rr = ss ? rs_of(ss, row) : 1.0f;
;                 u32x4 v[2];
; #pragma unroll
;                 for (int bj = 0; bj < 2; ++bj) {
;                     f32x4 a = __builtin_elementwise_max(acc[ai][bj][m][0], z) * rr, b = __builtin_elementwise_max(acc[ai][bj][m][1], z) * rr;
;                     v[bj] = pack8(a * a, b * b);
;                 }
;                 line_xchg(v[0], v[1], hb);
;                 bf16_t* p = O + (size_t)(srow0 + ai * HALF + m * 16) * ldc + scol;
;                 __builtin_nontemporal_store(v[0], (u32x4*)p); __builtin_nontemporal_store(v[1], (u32x4*)(p + (size_t)8 * ldc));
;             }
	v_max_f32_e32 v33, 0, v33
	v_max_f32_e32 v32, 0, v32
	v_max_f32_e32 v47, 0, v47
	v_max_f32_e32 v46, 0, v46
	v_max_f32_e32 v43, 0, v43
	v_max_f32_e32 v42, 0, v42
	v_max_f32_e32 v35, 0, v35
	v_max_f32_e32 v34, 0, v34
	v_max_f32_e32 v29, 0, v29
	v_max_f32_e32 v28, 0, v28
	v_max_f32_e32 v25, 0, v25
	v_max_f32_e32 v24, 0, v24
	v_max_f32_e32 v23, 0, v23
	v_max_f32_e32 v22, 0, v22
	v_max_f32_e32 v21, 0, v21
	v_max_f32_e32 v20, 0, v20
	v_max_f32_e32 v17, 0, v17
	v_max_f32_e32 v16, 0, v16
	v_max_f32_e32 v31, 0, v31
	v_max_f32_e32 v30, 0, v30
	v_max_f32_e32 v27, 0, v27
	v_max_f32_e32 v26, 0, v26
	v_max_f32_e32 v19, 0, v19
	v_max_f32_e32 v18, 0, v18
	v_max_f32_e32 v15, 0, v15
	v_max_f32_e32 v14, 0, v14
	v_max_f32_e32 v13, 0, v13
	v_max_f32_e32 v12, 0, v12
	v_max_f32_e32 v11, 0, v11
	v_max_f32_e32 v10, 0, v10
	v_max_f32_e32 v9, 0, v9
	v_max_f32_e32 v8, 0, v8
	v_max_f32_e32 v1, 0, v1
	v_max_f32_e32 v0, 0, v0
	v_max_f32_e32 v7, 0, v7
	v_max_f32_e32 v6, 0, v6
	v_max_f32_e32 v5, 0, v5
	v_max_f32_e32 v4, 0, v4
	v_max_f32_e32 v3, 0, v3
	v_max_f32_e32 v2, 0, v2
	v_mov_b32_e32 v96, v236
	v_pk_mul_f32 v[92:93], v[92:93], v[96:97] op_sel_hi:[1,0]
	v_pk_mul_f32 v[94:95], v[94:95], v[96:97] op_sel_hi:[1,0]
	v_pk_mul_f32 v[88:89], v[88:89], v[96:97] op_sel_hi:[1,0]
	v_pk_mul_f32 v[90:91], v[90:91], v[96:97] op_sel_hi:[1,0]
	v_pk_mul_f32 v[80:81], v[80:81], v[96:97] op_sel_hi:[1,0]
	v_pk_mul_f32 v[94:95], v[94:95], v[94:95]
	v_pk_mul_f32 v[92:93], v[92:93], v[92:93]
	v_pk_mul_f32 v[90:91], v[90:91], v[90:91]
	v_pk_mul_f32 v[88:89], v[88:89], v[88:89]
	v_pk_mul_f32 v[84:85], v[84:85], v[96:97] op_sel_hi:[1,0]
	v_pk_mul_f32 v[86:87], v[86:87], v[96:97] op_sel_hi:[1,0]
	v_pk_mul_f32 v[82:83], v[82:83], v[96:97] op_sel_hi:[1,0]
	v_pk_mul_f32 v[80:81], v[80:81], v[80:81]
	v_cvt_pk_bf16_f32 v92, v92, v93
	v_cvt_pk_bf16_f32 v93, v94, v95
	v_cvt_pk_bf16_f32 v88, v88, v89
	v_cvt_pk_bf16_f32 v89, v90, v91
	v_pk_mul_f32 v[86:87], v[86:87], v[86:87]
	v_pk_mul_f32 v[84:85], v[84:85], v[84:85]
	v_pk_mul_f32 v[82:83], v[82:83], v[82:83]
	v_cvt_pk_bf16_f32 v90, v84, v85
	v_cvt_pk_bf16_f32 v91, v86, v87
	v_cvt_pk_bf16_f32 v94, v80, v81
	s_nop 0
	v_cndmask_b32_e64 v81, v94, v88, s[2:3]
	v_cvt_pk_bf16_f32 v83, v82, v83
	v_cndmask_b32_e64 v82, v91, v93, s[2:3]
	v_cndmask_b32_e64 v80, v83, v89, s[2:3]
	v_mov_b32_dpp v96, v81 row_ror:8 row_mask:0xf bank_mask:0xf
	v_cndmask_b32_e64 v86, v88, v96, s[2:3]
	v_mov_b32_dpp v97, v80 row_ror:8 row_mask:0xf bank_mask:0xf
	v_or_b32_e32 v88, 32, v136
	v_cndmask_b32_e64 v87, v89, v97, s[2:3]
	v_ashrrev_i32_e32 v89, 31, v88
	v_cndmask_b32_e64 v84, v90, v92, s[2:3]
	v_lshlrev_b64 v[88:89], 14, v[88:89]
	v_mov_b32_dpp v82, v82 row_ror:8 row_mask:0xf bank_mask:0xf
	v_mov_b32_dpp v95, v84 row_ror:8 row_mask:0xf bank_mask:0xf
	v_lshl_add_u64 v[88:89], s[10:11], 0, v[88:89]
	v_cndmask_b32_e64 v84, v92, v95, s[2:3]
	v_cndmask_b32_e64 v85, v93, v82, s[2:3]
	v_lshl_add_u64 v[88:89], v[88:89], 0, v[122:123]
	global_store_dwordx4 v[88:89], v[84:87], off nt
	v_cndmask_b32_e64 v80, v95, v90, s[2:3]
	v_cndmask_b32_e64 v81, v82, v91, s[2:3]
	v_add_co_u32_e32 v84, vcc, s79, v88
	v_cndmask_b32_e64 v82, v96, v94, s[2:3]
	v_cndmask_b32_e64 v83, v97, v83, s[2:3]
	v_addc_co_u32_e32 v85, vcc, 0, v89, vcc
	global_store_dwordx4 v[84:85], v[80:83], off nt
	s_nop 1
	v_mov_b32_e32 v80, v237
	v_pk_mul_f32 v[76:77], v[76:77], v[80:81] op_sel_hi:[1,0]
	v_pk_mul_f32 v[78:79], v[78:79], v[80:81] op_sel_hi:[1,0]
	v_pk_mul_f32 v[72:73], v[72:73], v[80:81] op_sel_hi:[1,0]
	v_pk_mul_f32 v[74:75], v[74:75], v[80:81] op_sel_hi:[1,0]
	v_pk_mul_f32 v[64:65], v[64:65], v[80:81] op_sel_hi:[1,0]
	v_pk_mul_f32 v[78:79], v[78:79], v[78:79]
	v_pk_mul_f32 v[76:77], v[76:77], v[76:77]
	v_pk_mul_f32 v[74:75], v[74:75], v[74:75]
	v_pk_mul_f32 v[72:73], v[72:73], v[72:73]
	v_pk_mul_f32 v[68:69], v[68:69], v[80:81] op_sel_hi:[1,0]
	v_pk_mul_f32 v[70:71], v[70:71], v[80:81] op_sel_hi:[1,0]
	v_pk_mul_f32 v[66:67], v[66:67], v[80:81] op_sel_hi:[1,0]
	v_pk_mul_f32 v[64:65], v[64:65], v[64:65]
	v_cvt_pk_bf16_f32 v76, v76, v77
	v_cvt_pk_bf16_f32 v77, v78, v79
	v_cvt_pk_bf16_f32 v72, v72, v73
	v_cvt_pk_bf16_f32 v73, v74, v75
	v_pk_mul_f32 v[70:71], v[70:71], v[70:71]
	v_pk_mul_f32 v[68:69], v[68:69], v[68:69]
	v_pk_mul_f32 v[66:67], v[66:67], v[66:67]
	v_cvt_pk_bf16_f32 v74, v68, v69
	v_cvt_pk_bf16_f32 v75, v70, v71
	v_cvt_pk_bf16_f32 v78, v64, v65
	s_nop 0
	v_cndmask_b32_e64 v65, v78, v72, s[2:3]
	v_cvt_pk_bf16_f32 v67, v66, v67
	v_cndmask_b32_e64 v66, v75, v77, s[2:3]
	v_cndmask_b32_e64 v64, v67, v73, s[2:3]
	v_mov_b32_dpp v80, v65 row_ror:8 row_mask:0xf bank_mask:0xf
	v_cndmask_b32_e64 v70, v72, v80, s[2:3]
	v_mov_b32_dpp v81, v64 row_ror:8 row_mask:0xf bank_mask:0xf
	v_or_b32_e32 v72, 48, v136
	v_cndmask_b32_e64 v71, v73, v81, s[2:3]
	v_ashrrev_i32_e32 v73, 31, v72
	v_cndmask_b32_e64 v68, v74, v76, s[2:3]
	v_lshlrev_b64 v[72:73], 14, v[72:73]
	v_mov_b32_dpp v66, v66 row_ror:8 row_mask:0xf bank_mask:0xf
	v_mov_b32_dpp v79, v68 row_ror:8 row_mask:0xf bank_mask:0xf
	v_lshl_add_u64 v[72:73], s[10:11], 0, v[72:73]
	v_cndmask_b32_e64 v68, v76, v79, s[2:3]
	v_cndmask_b32_e64 v69, v77, v66, s[2:3]
	v_lshl_add_u64 v[72:73], v[72:73], 0, v[122:123]
	global_store_dwordx4 v[72:73], v[68:71], off nt
	v_cndmask_b32_e64 v64, v79, v74, s[2:3]
	v_cndmask_b32_e64 v65, v66, v75, s[2:3]
	v_add_co_u32_e32 v68, vcc, s79, v72
	v_cndmask_b32_e64 v66, v80, v78, s[2:3]
	v_cndmask_b32_e64 v67, v81, v67, s[2:3]
	v_addc_co_u32_e32 v69, vcc, 0, v73, vcc
	global_store_dwordx4 v[68:69], v[64:67], off nt
	s_nop 1
	s_mov_b32 s0, 0x200000
	v_mov_b32_e32 v64, v238
	v_pk_mul_f32 v[60:61], v[60:61], v[64:65] op_sel_hi:[1,0]
; __device__ __forceinline__ u32x4 pack8(f32x4 a, f32x4 b) { u32x4 w; w.x = cvt_pk_bf16(a[0], a[1]); w.y = cvt_pk_bf16(a[2], a[3]); w.z = cvt_pk_bf16(b[0], b[1]); w.w = cvt_pk_bf16(b[2], b[3]); return w; }
; __device__ __forceinline__ float rs_of(const float* ss, int row) { return 1.0f / sqrtf(ss[row] * (1.0f / 2048.0f) + 1e-5f); }
;     __device__ __forceinline__ void operator()(const f32x4 (&acc)[2][2][4][2], const Unit& u, int wr, int wc, int fr, int fq) const {
;     ...
;             for (int m = 0; m < 4; ++m) {
;                 const int row = row0 + ai * HALF + m * 16; const float rr = ss ? rs_of(ss, row) : 1.0f;
;                 u32x4 v[2];
; #pragma unroll
;                 for (int bj = 0; bj < 2; ++bj) {
;                     f32x4 a = __builtin_elementwise_max(acc[ai][bj][m][0], z) * rr, b = __builtin_elementwise_max(acc[ai][bj][m][1], z) * rr;
;                     v[bj] = pack8(a * a, b * b);
;                 }
;                 line_xchg(v[0], v[1], hb);
;                 bf16_t* p = O + (size_t)(srow0 + ai * HALF + m * 16) * ldc + scol;
;                 __builtin_nontemporal_store(v[0], (u32x4*)p); __builtin_nontemporal_store(v[1], (u32x4*)(p + (size_t)8 * ldc));
;             }
	v_pk_mul_f32 v[62:63], v[62:63], v[64:65] op_sel_hi:[1,0]
	v_pk_mul_f32 v[56:57], v[56:57], v[64:65] op_sel_hi:[1,0]
	v_pk_mul_f32 v[58:59], v[58:59], v[64:65] op_sel_hi:[1,0]
	v_pk_mul_f32 v[48:49], v[48:49], v[64:65] op_sel_hi:[1,0]
	v_pk_mul_f32 v[62:63], v[62:63], v[62:63]
	v_pk_mul_f32 v[60:61], v[60:61], v[60:61]
	v_pk_mul_f32 v[58:59], v[58:59], v[58:59]
	v_pk_mul_f32 v[56:57], v[56:57], v[56:57]
	v_pk_mul_f32 v[52:53], v[52:53], v[64:65] op_sel_hi:[1,0]
	v_pk_mul_f32 v[54:55], v[54:55], v[64:65] op_sel_hi:[1,0]
	v_pk_mul_f32 v[50:51], v[50:51], v[64:65] op_sel_hi:[1,0]
	v_pk_mul_f32 v[48:49], v[48:49], v[48:49]
	v_cvt_pk_bf16_f32 v60, v60, v61
	v_cvt_pk_bf16_f32 v61, v62, v63
	v_cvt_pk_bf16_f32 v56, v56, v57
	v_cvt_pk_bf16_f32 v57, v58, v59
	v_pk_mul_f32 v[54:55], v[54:55], v[54:55]
	v_pk_mul_f32 v[52:53], v[52:53], v[52:53]
	v_pk_mul_f32 v[50:51], v[50:51], v[50:51]
	v_cvt_pk_bf16_f32 v58, v52, v53
	v_cvt_pk_bf16_f32 v59, v54, v55
	v_cvt_pk_bf16_f32 v62, v48, v49
	s_nop 0
	v_cndmask_b32_e64 v49, v62, v56, s[2:3]
	v_cvt_pk_bf16_f32 v51, v50, v51
	v_cndmask_b32_e64 v50, v59, v61, s[2:3]
	v_cndmask_b32_e64 v48, v51, v57, s[2:3]
	v_cndmask_b32_e64 v52, v58, v60, s[2:3]
	v_mov_b32_dpp v64, v49 row_ror:8 row_mask:0xf bank_mask:0xf
	v_mov_b32_dpp v50, v50 row_ror:8 row_mask:0xf bank_mask:0xf
	v_mov_b32_dpp v63, v52 row_ror:8 row_mask:0xf bank_mask:0xf
	v_mov_b32_dpp v65, v48 row_ror:8 row_mask:0xf bank_mask:0xf
	v_cndmask_b32_e64 v54, v56, v64, s[2:3]
	v_add_co_u32_e32 v56, vcc, s0, v120
	v_cndmask_b32_e64 v52, v60, v63, s[2:3]
	v_cndmask_b32_e64 v53, v61, v50, s[2:3]
	v_cndmask_b32_e64 v55, v57, v65, s[2:3]
	v_addc_co_u32_e32 v57, vcc, 0, v121, vcc
	s_mov_b32 s0, 0x220000
	global_store_dwordx4 v[56:57], v[52:55], off nt
	v_cndmask_b32_e64 v48, v63, v58, s[2:3]
	v_cndmask_b32_e64 v49, v50, v59, s[2:3]
	v_add_co_u32_e32 v52, vcc, s0, v120
	v_cndmask_b32_e64 v50, v64, v62, s[2:3]
	v_cndmask_b32_e64 v51, v65, v51, s[2:3]
	v_addc_co_u32_e32 v53, vcc, 0, v121, vcc
	global_store_dwordx4 v[52:53], v[48:51], off nt
	s_nop 1
	s_mov_b32 s0, 0x240000
	v_mov_b32_e32 v48, v239
	v_pk_mul_f32 v[44:45], v[44:45], v[48:49] op_sel_hi:[1,0]
	v_pk_mul_f32 v[40:41], v[40:41], v[48:49] op_sel_hi:[1,0]
	v_pk_mul_f32 v[36:37], v[36:37], v[48:49] op_sel_hi:[1,0]
	v_pk_mul_f32 v[38:39], v[38:39], v[48:49] op_sel_hi:[1,0]
	v_pk_mul_f32 v[32:33], v[32:33], v[48:49] op_sel_hi:[1,0]
	v_pk_mul_f32 v[46:47], v[46:47], v[48:49] op_sel_hi:[1,0]
	v_pk_mul_f32 v[42:43], v[42:43], v[48:49] op_sel_hi:[1,0]
	v_pk_mul_f32 v[44:45], v[44:45], v[44:45]
	v_pk_mul_f32 v[40:41], v[40:41], v[40:41]
	v_pk_mul_f32 v[34:35], v[34:35], v[48:49] op_sel_hi:[1,0]
	v_pk_mul_f32 v[38:39], v[38:39], v[38:39]
	v_pk_mul_f32 v[36:37], v[36:37], v[36:37]
	v_pk_mul_f32 v[32:33], v[32:33], v[32:33]
	v_pk_mul_f32 v[46:47], v[46:47], v[46:47]
	v_pk_mul_f32 v[42:43], v[42:43], v[42:43]
	v_cvt_pk_bf16_f32 v44, v44, v45
	v_cvt_pk_bf16_f32 v45, v46, v47
	v_cvt_pk_bf16_f32 v40, v40, v41
	v_pk_mul_f32 v[34:35], v[34:35], v[34:35]
	v_cvt_pk_bf16_f32 v41, v42, v43
	v_cvt_pk_bf16_f32 v36, v36, v37
	v_cvt_pk_bf16_f32 v37, v38, v39
	v_cvt_pk_bf16_f32 v38, v32, v33
	s_nop 0
	v_cndmask_b32_e64 v33, v38, v40, s[2:3]
	v_cvt_pk_bf16_f32 v39, v34, v35
	v_cndmask_b32_e64 v34, v37, v45, s[2:3]
	v_cndmask_b32_e64 v32, v39, v41, s[2:3]
	v_cndmask_b32_e64 v35, v36, v44, s[2:3]
	v_mov_b32_dpp v46, v33 row_ror:8 row_mask:0xf bank_mask:0xf
	v_mov_b32_dpp v43, v34 row_ror:8 row_mask:0xf bank_mask:0xf
	v_mov_b32_dpp v42, v35 row_ror:8 row_mask:0xf bank_mask:0xf
	v_mov_b32_dpp v47, v32 row_ror:8 row_mask:0xf bank_mask:0xf
	v_cndmask_b32_e64 v34, v40, v46, s[2:3]
	v_add_co_u32_e32 v40, vcc, s0, v120
	v_cndmask_b32_e64 v32, v44, v42, s[2:3]
	v_cndmask_b32_e64 v33, v45, v43, s[2:3]
	v_cndmask_b32_e64 v35, v41, v47, s[2:3]
	v_addc_co_u32_e32 v41, vcc, 0, v121, vcc
	s_mov_b32 s0, 0x260000
	global_store_dwordx4 v[40:41], v[32:35], off nt
	v_cndmask_b32_e64 v36, v42, v36, s[2:3]
	v_cndmask_b32_e64 v37, v43, v37, s[2:3]
	v_add_co_u32_e32 v32, vcc, s0, v120
	v_cndmask_b32_e64 v38, v46, v38, s[2:3]
	v_cndmask_b32_e64 v39, v47, v39, s[2:3]
	v_addc_co_u32_e32 v33, vcc, 0, v121, vcc
	global_store_dwordx4 v[32:33], v[36:39], off nt
	s_nop 1
	s_mov_b32 s0, 0x280000
	v_mov_b32_e32 v32, v240
; __device__ __forceinline__ u32x4 pack8(f32x4 a, f32x4 b) { u32x4 w; w.x = cvt_pk_bf16(a[0], a[1]); w.y = cvt_pk_bf16(a[2], a[3]); w.z = cvt_pk_bf16(b[0], b[1]); w.w = cvt_pk_bf16(b[2], b[3]); return w; }
; __device__ __forceinline__ float rs_of(const float* ss, int row) { return 1.0f / sqrtf(ss[row] * (1.0f / 2048.0f) + 1e-5f); }
;     __device__ __forceinline__ void operator()(const f32x4 (&acc)[2][2][4][2], const Unit& u, int wr, int wc, int fr, int fq) const {
;     ...
;             for (int m = 0; m < 4; ++m) {
;                 const int row = row0 + ai * HALF + m * 16; const float rr = ss ? rs_of(ss, row) : 1.0f;
;                 u32x4 v[2];
; #pragma unroll
;                 for (int bj = 0; bj < 2; ++bj) {
;                     f32x4 a = __builtin_elementwise_max(acc[ai][bj][m][0], z) * rr, b = __builtin_elementwise_max(acc[ai][bj][m][1], z) * rr;
;                     v[bj] = pack8(a * a, b * b);
;                 }
;                 line_xchg(v[0], v[1], hb);
;                 bf16_t* p = O + (size_t)(srow0 + ai * HALF + m * 16) * ldc + scol;
;                 __builtin_nontemporal_store(v[0], (u32x4*)p); __builtin_nontemporal_store(v[1], (u32x4*)(p + (size_t)8 * ldc));
;             }
	v_pk_mul_f32 v[28:29], v[28:29], v[32:33] op_sel_hi:[1,0]
	v_pk_mul_f32 v[24:25], v[24:25], v[32:33] op_sel_hi:[1,0]
	v_pk_mul_f32 v[20:21], v[20:21], v[32:33] op_sel_hi:[1,0]
	v_pk_mul_f32 v[22:23], v[22:23], v[32:33] op_sel_hi:[1,0]
	v_pk_mul_f32 v[16:17], v[16:17], v[32:33] op_sel_hi:[1,0]
	v_pk_mul_f32 v[30:31], v[30:31], v[32:33] op_sel_hi:[1,0]
	v_pk_mul_f32 v[26:27], v[26:27], v[32:33] op_sel_hi:[1,0]
	v_pk_mul_f32 v[28:29], v[28:29], v[28:29]
	v_pk_mul_f32 v[24:25], v[24:25], v[24:25]
	v_pk_mul_f32 v[18:19], v[18:19], v[32:33] op_sel_hi:[1,0]
	v_pk_mul_f32 v[22:23], v[22:23], v[22:23]
	v_pk_mul_f32 v[20:21], v[20:21], v[20:21]
	v_pk_mul_f32 v[16:17], v[16:17], v[16:17]
	v_pk_mul_f32 v[30:31], v[30:31], v[30:31]
	v_pk_mul_f32 v[26:27], v[26:27], v[26:27]
	v_cvt_pk_bf16_f32 v28, v28, v29
	v_cvt_pk_bf16_f32 v29, v30, v31
	v_cvt_pk_bf16_f32 v24, v24, v25
	v_pk_mul_f32 v[18:19], v[18:19], v[18:19]
	v_cvt_pk_bf16_f32 v25, v26, v27
	v_cvt_pk_bf16_f32 v20, v20, v21
	v_cvt_pk_bf16_f32 v21, v22, v23
	v_cvt_pk_bf16_f32 v22, v16, v17
	s_nop 0
	v_cndmask_b32_e64 v17, v22, v24, s[2:3]
	v_cvt_pk_bf16_f32 v23, v18, v19
	v_cndmask_b32_e64 v18, v21, v29, s[2:3]
	v_cndmask_b32_e64 v16, v23, v25, s[2:3]
	v_cndmask_b32_e64 v19, v20, v28, s[2:3]
	v_mov_b32_dpp v30, v17 row_ror:8 row_mask:0xf bank_mask:0xf
	v_mov_b32_dpp v27, v18 row_ror:8 row_mask:0xf bank_mask:0xf
	v_mov_b32_dpp v26, v19 row_ror:8 row_mask:0xf bank_mask:0xf
	v_mov_b32_dpp v31, v16 row_ror:8 row_mask:0xf bank_mask:0xf
	v_cndmask_b32_e64 v18, v24, v30, s[2:3]
	v_add_co_u32_e32 v24, vcc, s0, v120
	v_cndmask_b32_e64 v16, v28, v26, s[2:3]
	v_cndmask_b32_e64 v17, v29, v27, s[2:3]
	v_cndmask_b32_e64 v19, v25, v31, s[2:3]
	v_addc_co_u32_e32 v25, vcc, 0, v121, vcc
	s_mov_b32 s0, 0x2a0000
	global_store_dwordx4 v[24:25], v[16:19], off nt
	v_cndmask_b32_e64 v20, v26, v20, s[2:3]
	v_cndmask_b32_e64 v21, v27, v21, s[2:3]
	v_add_co_u32_e32 v16, vcc, s0, v120
	v_cndmask_b32_e64 v22, v30, v22, s[2:3]
	v_cndmask_b32_e64 v23, v31, v23, s[2:3]
	v_addc_co_u32_e32 v17, vcc, 0, v121, vcc
	global_store_dwordx4 v[16:17], v[20:23], off nt
	s_nop 1
	s_mov_b64 s[0:1], -1
	v_mov_b32_e32 v16, v241
	v_pk_mul_f32 v[12:13], v[12:13], v[16:17] op_sel_hi:[1,0]
	v_pk_mul_f32 v[14:15], v[14:15], v[16:17] op_sel_hi:[1,0]
	v_pk_mul_f32 v[8:9], v[8:9], v[16:17] op_sel_hi:[1,0]
	v_pk_mul_f32 v[10:11], v[10:11], v[16:17] op_sel_hi:[1,0]
	v_pk_mul_f32 v[0:1], v[0:1], v[16:17] op_sel_hi:[1,0]
	v_pk_mul_f32 v[14:15], v[14:15], v[14:15]
	v_pk_mul_f32 v[12:13], v[12:13], v[12:13]
	v_pk_mul_f32 v[10:11], v[10:11], v[10:11]
	v_pk_mul_f32 v[8:9], v[8:9], v[8:9]
	v_pk_mul_f32 v[4:5], v[4:5], v[16:17] op_sel_hi:[1,0]
	v_pk_mul_f32 v[6:7], v[6:7], v[16:17] op_sel_hi:[1,0]
	v_pk_mul_f32 v[2:3], v[2:3], v[16:17] op_sel_hi:[1,0]
	v_pk_mul_f32 v[0:1], v[0:1], v[0:1]
	v_cvt_pk_bf16_f32 v12, v12, v13
	v_cvt_pk_bf16_f32 v13, v14, v15
	v_cvt_pk_bf16_f32 v8, v8, v9
	v_cvt_pk_bf16_f32 v9, v10, v11
	v_pk_mul_f32 v[6:7], v[6:7], v[6:7]
	v_pk_mul_f32 v[4:5], v[4:5], v[4:5]
	v_pk_mul_f32 v[2:3], v[2:3], v[2:3]
	v_cvt_pk_bf16_f32 v10, v4, v5
	v_cvt_pk_bf16_f32 v11, v6, v7
	v_cvt_pk_bf16_f32 v14, v0, v1
	s_nop 0
	v_cndmask_b32_e64 v1, v14, v8, s[2:3]
	v_cvt_pk_bf16_f32 v3, v2, v3
	v_cndmask_b32_e64 v2, v11, v13, s[2:3]
	v_cndmask_b32_e64 v0, v3, v9, s[2:3]
	v_cndmask_b32_e64 v4, v10, v12, s[2:3]
	v_mov_b32_dpp v16, v1 row_ror:8 row_mask:0xf bank_mask:0xf
	v_mov_b32_dpp v2, v2 row_ror:8 row_mask:0xf bank_mask:0xf
	v_mov_b32_dpp v15, v4 row_ror:8 row_mask:0xf bank_mask:0xf
	v_mov_b32_dpp v17, v0 row_ror:8 row_mask:0xf bank_mask:0xf
	v_cndmask_b32_e64 v6, v8, v16, s[2:3]
	v_add_co_u32_e32 v8, vcc, 0x2c0000, v120
	v_cndmask_b32_e64 v4, v12, v15, s[2:3]
	v_cndmask_b32_e64 v5, v13, v2, s[2:3]
	v_cndmask_b32_e64 v7, v9, v17, s[2:3]
	v_addc_co_u32_e32 v9, vcc, 0, v121, vcc
	global_store_dwordx4 v[8:9], v[4:7], off nt
	v_cndmask_b32_e64 v0, v15, v10, s[2:3]
	v_cndmask_b32_e64 v1, v2, v11, s[2:3]
	v_add_co_u32_e32 v4, vcc, 0x2e0000, v120
	v_cndmask_b32_e64 v2, v16, v14, s[2:3]
	s_nop 0
	v_addc_co_u32_e32 v5, vcc, 0, v121, vcc
	v_cndmask_b32_e64 v3, v17, v3, s[2:3]
	s_andn2_b64 vcc, exec, s[4:5]
	global_store_dwordx4 v[4:5], v[0:3], off nt
	s_cbranch_vccnz .LBB0_702
	s_andn2_b64 vcc, exec, s[8:9]
	s_cbranch_vccnz .LBB0_701
	s_barrier
	s_branch .LBB0_701
